# v074: v073 + diff fast path back edge rotated (next pair's entry test and address set-up before the closing barrier, re-enter at the QK burst)
# speedup vs baseline: 1.0264x; 1.0061x over previous
; #define LAS __attribute__((address_space(3)))
; template <int DQK, int DKA, int DV> ...
;     ...
;         if (64 * t <= qlast) {
;             f32x16 p0, p1; s16x4 vlo[8], vhi[8]; bf16x8 pf[4];
;             LAS const unsigned char* vb = lds + C::VOFF + (t & 3) * C::VBYTES + voff;
;             __builtin_amdgcn_sched_barrier(0);
;             __builtin_amdgcn_s_setprio(3);
; #pragma unroll
;             for (int d0 = 0; d0 < ND; ++d0) {
;                 if (d0 == 0) { p0 = MFMA32(kf[0], qr[0], negm); p1 = MFMA32(kf[1], qr[0], negm); }
;                 else { p0 = MFMA32(kf[2 * d0], qr[d0], p0); p1 = MFMA32(kf[2 * d0 + 1], qr[d0], p1); }
;             }
;             __builtin_amdgcn_s_setprio(0);
;             __builtin_amdgcn_sched_barrier(0);
;             ATT_VFRAG(0);
;             __builtin_amdgcn_sched_barrier(0);
;             if (64 * t + 63 > q0 + 32 * wid) {
;                 const int kvb = 64 * t + 4 * hi;
; #pragma unroll
;                 for (int i = 0; i < 16; ++i) { const int kv = kvb + (i & 3) + 8 * (i >> 2); if (kv > qabs) p0[i] = -INFINITY; if (kv + 32 > qabs) p1[i] = -INFINITY; }
;             }
;             float mxa = MAX3F(p0[0], p0[1], p1[0]), mxb = MAX3F(p0[2], p0[3], p1[1]); mxa = MAX3F(mxa, p1[2], p1[3]);
; #pragma unroll
;             for (int i = 4; i < 16; i += 4) { mxa = MAX3F(mxa, p0[i], p0[i + 1]); mxb = MAX3F(mxb, p0[i + 2], p0[i + 3]); mxa = MAX3F(mxa, p1[i], p1[i + 1]); mxb = MAX3F(mxb, p1[i + 2], p1[i + 3]); }
;             float mx = fmaxf(mxa, mxb);
;             { auto rr = __builtin_amdgcn_permlane32_swap(__float_as_uint(mx), __float_as_uint(mx), false, false); mx = fmaxf(__uint_as_float(rr[0]), __uint_as_float(rr[1])); }
;             if (!NEGM) mx -= m;
;             if (t == 0) {
;                 m = mx;
;                 if (NEGM) {
; #pragma unroll
;                     for (int i = 0; i < 16; ++i) { p0[i] -= mx; p1[i] -= mx; }
; #pragma unroll
;                     for (int i = 0; i < 16; ++i) negm[i] = -m;
;                 }
;             } else if (__any(mx > RESC_THR)) {
;     ...
;             { float rs = 0.f;
; #pragma unroll
;               for (int i = 0; i < 16; ++i) { p0[i] = __builtin_amdgcn_exp2f(NEGM ? p0[i] : p0[i] - m); p1[i] = __builtin_amdgcn_exp2f(NEGM ? p1[i] : p1[i] - m); rs += p0[i] + p1[i]; }
;               l += rs;
; #pragma unroll
;               for (int s = 0; s < 2; ++s) { u32x4 w0, w1;
.Lfast_d_qk:
	v_mfma_f32_32x32x16_bf16 v[80:95], v[144:147], v[112:115], v[0:15]
	ds_read_b128 v[144:147], v249
	v_mfma_f32_32x32x16_bf16 v[96:111], v[152:155], v[112:115], v[0:15]
	ds_read_b128 v[152:155], v249 offset:4608
	v_mfma_f32_32x32x16_bf16 v[80:95], v[140:143], v[116:119], v[80:95]
	ds_read_b128 v[140:143], v249 offset:32
	v_mfma_f32_32x32x16_bf16 v[96:111], v[148:151], v[116:119], v[96:111]
	ds_read_b128 v[148:151], v249 offset:4640
	v_mfma_f32_32x32x16_bf16 v[80:95], v[156:159], v[120:123], v[80:95]
	ds_read_b128 v[156:159], v249 offset:64
	v_mfma_f32_32x32x16_bf16 v[96:111], v[168:171], v[120:123], v[96:111]
	ds_read_b128 v[168:171], v249 offset:4672
	v_mfma_f32_32x32x16_bf16 v[80:95], v[160:163], v[124:127], v[80:95]
	ds_read_b128 v[160:163], v249 offset:96
	v_mfma_f32_32x32x16_bf16 v[96:111], v[164:167], v[124:127], v[96:111]
	ds_read_b128 v[164:167], v249 offset:4704
	s_setprio 0
	s_add_i32 s80, s1, -1
	s_add_i32 s23, s1, -2
	s_and_b32 s22, s80, 3
	s_mulk_i32 s22, 0x2400
	v_add_u32_e32 v253, s22, v217
	s_waitcnt vmcnt(0)
	ds_write_b128 v253, v[128:131]
	s_and_b32 s22, s23, 3
	s_mulk_i32 s22, 0x5000
	v_add_u32_e32 v253, s22, v227
	ds_write_b128 v253, v[132:135] offset:36864
	ds_write_b128 v253, v[136:139] offset:47104
	global_load_dwordx4 v[128:131], v[218:219], off
	v_add_co_u32_e32 v254, vcc, 0x2000, v220
	s_nop 1
	v_addc_co_u32_e32 v255, vcc, 0, v221, vcc
	global_load_dwordx4 v[132:135], v[220:221], off
	global_load_dwordx4 v[136:139], v[254:255], off
	v_max_f32_e32 v232, v81, v81
	v_max_f32_e32 v233, v80, v80
	v_max_f32_e32 v232, v233, v232
	v_max3_f32 v233, v82, v83, v97
	v_max3_f32 v232, v232, v96, v98
	v_max3_f32 v232, v232, v99, v84
	v_max3_f32 v233, v233, v86, v87
	v_max3_f32 v232, v232, v85, v100
	v_max3_f32 v233, v233, v102, v103
	v_max3_f32 v232, v232, v101, v88
	v_max3_f32 v233, v233, v90, v91
	v_max3_f32 v232, v232, v89, v104
	v_max3_f32 v233, v233, v106, v107
	v_max3_f32 v232, v232, v105, v92
	v_max3_f32 v233, v233, v94, v95
	v_max3_f32 v232, v232, v93, v108
	v_max3_f32 v233, v233, v110, v111
	v_max3_f32 v232, v232, v109, v233
	v_mov_b32_e32 v233, v232
	s_nop 1
	v_permlane32_swap_b32_e32 v232, v233
	v_max_f32_e32 v233, v233, v233
	v_max_f32_e32 v232, v232, v232
	v_max_f32_e32 v232, v232, v233
	v_cmp_lt_f32_e32 vcc, s62, v232
	s_cbranch_vccnz .Lfast_d_bail1
	s_waitcnt lgkmcnt(0)
	v_exp_f32_e32 v80, v80
	v_exp_f32_e32 v96, v96
	v_exp_f32_e32 v81, v81
	v_exp_f32_e32 v97, v97
	v_mfma_f32_32x32x16_bf16 v[172:187], v[144:147], v[112:115], v[0:15]
	ds_read_b64_tr_b16 v[144:145], v210 offset:36864
	ds_read_b64_tr_b16 v[146:147], v210 offset:39424
	v_exp_f32_e32 v82, v82
	v_exp_f32_e32 v98, v98
	v_exp_f32_e32 v83, v83
	v_exp_f32_e32 v99, v99
	v_mfma_f32_32x32x16_bf16 v[188:203], v[152:155], v[112:115], v[0:15]
	ds_read_b64_tr_b16 v[152:153], v210 offset:36928
	ds_read_b64_tr_b16 v[154:155], v210 offset:39488
	v_exp_f32_e32 v84, v84
	v_exp_f32_e32 v100, v100
	v_exp_f32_e32 v85, v85
	v_exp_f32_e32 v101, v101
	v_mfma_f32_32x32x16_bf16 v[172:187], v[140:143], v[116:119], v[172:187]
	ds_read_b64_tr_b16 v[140:141], v210 offset:41984
	ds_read_b64_tr_b16 v[142:143], v210 offset:44544
	v_exp_f32_e32 v86, v86
	v_exp_f32_e32 v102, v102
	v_exp_f32_e32 v87, v87
	v_exp_f32_e32 v103, v103
	v_mfma_f32_32x32x16_bf16 v[188:203], v[148:151], v[116:119], v[188:203]
	ds_read_b64_tr_b16 v[148:149], v210 offset:42048
	ds_read_b64_tr_b16 v[150:151], v210 offset:44608
	v_exp_f32_e32 v88, v88
	v_exp_f32_e32 v104, v104
	v_exp_f32_e32 v89, v89
	v_exp_f32_e32 v105, v105
	v_mfma_f32_32x32x16_bf16 v[172:187], v[156:159], v[120:123], v[172:187]
	ds_read_b64_tr_b16 v[156:157], v210 offset:47104
	ds_read_b64_tr_b16 v[158:159], v210 offset:49664
	v_exp_f32_e32 v90, v90
	v_exp_f32_e32 v106, v106
	v_exp_f32_e32 v91, v91
	v_exp_f32_e32 v107, v107
	v_mfma_f32_32x32x16_bf16 v[188:203], v[168:171], v[120:123], v[188:203]
	ds_read_b64_tr_b16 v[168:169], v210 offset:47168
	ds_read_b64_tr_b16 v[170:171], v210 offset:49728
	v_exp_f32_e32 v92, v92
	v_exp_f32_e32 v108, v108
	v_exp_f32_e32 v93, v93
	v_exp_f32_e32 v109, v109
	v_mfma_f32_32x32x16_bf16 v[172:187], v[160:163], v[124:127], v[172:187]
	ds_read_b64_tr_b16 v[160:161], v210 offset:52224
	ds_read_b64_tr_b16 v[162:163], v210 offset:54784
	v_exp_f32_e32 v94, v94
	v_exp_f32_e32 v110, v110
	v_exp_f32_e32 v95, v95
	v_exp_f32_e32 v111, v111
	v_mfma_f32_32x32x16_bf16 v[188:203], v[164:167], v[124:127], v[188:203]
	ds_read_b64_tr_b16 v[164:165], v210 offset:52288
	ds_read_b64_tr_b16 v[166:167], v210 offset:54848
	v_cvt_pk_bf16_f32 v232, v80, v81
	v_cvt_pk_bf16_f32 v233, v82, v83
	v_cvt_pk_bf16_f32 v234, v84, v85
	v_cvt_pk_bf16_f32 v235, v86, v87
	v_cvt_pk_bf16_f32 v236, v96, v97
	v_cvt_pk_bf16_f32 v237, v98, v99
	v_cvt_pk_bf16_f32 v238, v100, v101
	v_cvt_pk_bf16_f32 v239, v102, v103
	v_cvt_pk_bf16_f32 v240, v88, v89
	v_cvt_pk_bf16_f32 v241, v90, v91
	v_cvt_pk_bf16_f32 v242, v92, v93
	v_cvt_pk_bf16_f32 v243, v94, v95
	v_cvt_pk_bf16_f32 v244, v104, v105
	v_cvt_pk_bf16_f32 v245, v106, v107
	v_cvt_pk_bf16_f32 v246, v108, v109
	v_cvt_pk_bf16_f32 v247, v110, v111
	v_max_f32_e32 v250, v173, v173
	v_max_f32_e32 v251, v172, v172
	v_max_f32_e32 v250, v251, v250
	v_max3_f32 v251, v174, v175, v189
	v_max3_f32 v250, v250, v188, v190
	v_max3_f32 v250, v250, v191, v176
	v_max3_f32 v251, v251, v178, v179
	v_max3_f32 v250, v250, v177, v192
	v_max3_f32 v251, v251, v194, v195
	v_max3_f32 v250, v250, v193, v180
	v_max3_f32 v251, v251, v182, v183
	v_max3_f32 v250, v250, v181, v196
	v_max3_f32 v251, v251, v198, v199
	v_max3_f32 v250, v250, v197, v184
	v_max3_f32 v251, v251, v186, v187
	v_max3_f32 v250, v250, v185, v200
	v_max3_f32 v251, v251, v202, v203
	v_max3_f32 v250, v250, v201, v251
	v_mov_b32_e32 v251, v250
	s_nop 1
	v_permlane32_swap_b32_e32 v250, v251
	v_max_f32_e32 v251, v251, v251
	v_max_f32_e32 v250, v250, v250
	v_max_f32_e32 v250, v250, v251
	v_cmp_lt_f32_e32 vcc, s62, v250
	s_cbranch_vccnz .Lfast_d_bail2
; __device__ __forceinline__ unsigned cvtpk_s(float lo, float hi) { f32x2_t v = {lo, hi}; bf16x2_t b = __builtin_convertvector(v, bf16x2_t); return __builtin_bit_cast(unsigned, b); }
; #define ATT_KFRAG(slot) do { LAS const unsigned char* kb_ = lds + (slot) * C::KBYTES + koff; \
;     _Pragma("unroll") for (int d0 = 0; d0 < ND; ++d0) { kf[2 * d0] = *(LAS const bf16x8*)(kb_ + 32 * d0); kf[2 * d0 + 1] = *(LAS const bf16x8*)(kb_ + 32 * KP + 32 * d0); } } while (0)
; #define ATT_VFRAG(vv) do { _Pragma("unroll") for (int j = 0; j < 2; ++j) _Pragma("unroll") for (int s4 = 0; s4 < 4; ++s4) { \
;         vlo[j * 4 + s4] = vtr(vb + (16 * s4) * VP + 64 * ((vv) + j)); vhi[j * 4 + s4] = vtr(vb + (16 * s4 + 8) * VP + 64 * ((vv) + j)); } } while (0)
; template <int DQK, int DKA, int DV> ...
;     ...
;             { float rs = 0.f;
; #pragma unroll
;               for (int i = 0; i < 16; ++i) { p0[i] = __builtin_amdgcn_exp2f(NEGM ? p0[i] : p0[i] - m); p1[i] = __builtin_amdgcn_exp2f(NEGM ? p1[i] : p1[i] - m); rs += p0[i] + p1[i]; }
;               l += rs;
; #pragma unroll
;               for (int s = 0; s < 2; ++s) { u32x4 w0, w1;
;                 w0.x = cvtpk_s(p0[8 * s], p0[8 * s + 1]); w0.y = cvtpk_s(p0[8 * s + 2], p0[8 * s + 3]); w0.z = cvtpk_s(p0[8 * s + 4], p0[8 * s + 5]); w0.w = cvtpk_s(p0[8 * s + 6], p0[8 * s + 7]);
;                 w1.x = cvtpk_s(p1[8 * s], p1[8 * s + 1]); w1.y = cvtpk_s(p1[8 * s + 2], p1[8 * s + 3]); w1.z = cvtpk_s(p1[8 * s + 4], p1[8 * s + 5]); w1.w = cvtpk_s(p1[8 * s + 6], p1[8 * s + 7]);
;                 pf[s] = __builtin_bit_cast(bf16x8, w0); pf[2 + s] = __builtin_bit_cast(bf16x8, w1); } }
;             __builtin_amdgcn_sched_barrier(0);
;             if (NV == 2) {
;                 __builtin_amdgcn_s_setprio(3); ATT_PV(0); __builtin_amdgcn_s_setprio(0);
;                 __builtin_amdgcn_sched_barrier(0);
;                 if (t + 1 < NT) ATT_KFRAG(ks1);
;             } else {
;                 __builtin_amdgcn_s_setprio(3); ATT_PV(0); __builtin_amdgcn_s_setprio(0);
;                 __builtin_amdgcn_sched_barrier(0);
;                 ATT_VFRAG(2);
;                 __builtin_amdgcn_sched_barrier(0);
;                 __builtin_amdgcn_s_setprio(3); ATT_PV(2); __builtin_amdgcn_s_setprio(0);
;                 __builtin_amdgcn_sched_barrier(0);
;                 if (t + 1 < NT) ATT_KFRAG(ks1);
;             }
	s_setprio 0
	s_waitcnt lgkmcnt(0)
	v_mfma_f32_32x32x16_bf16 v[32:47], v[144:147], v[232:235], v[32:47]
	v_lshl_add_u64 v[218:219], v[218:219], 0, s[10:11]
	v_lshl_add_u64 v[220:221], v[220:221], 0, s[8:9]
	s_add_i32 s23, s1, -1
	s_and_b32 s22, s1, 3
	s_mulk_i32 s22, 0x2400
	v_add_u32_e32 v253, s22, v217
	s_waitcnt vmcnt(0)
	ds_write_b128 v253, v[128:131]
	s_and_b32 s22, s23, 3
	s_mulk_i32 s22, 0x5000
	v_mfma_f32_32x32x16_bf16 v[16:31], v[152:155], v[232:235], v[16:31]
	v_add_u32_e32 v253, s22, v227
	ds_write_b128 v253, v[132:135] offset:36864
	ds_write_b128 v253, v[136:139] offset:47104
	global_load_dwordx4 v[128:131], v[218:219], off
	v_add_co_u32_e32 v254, vcc, 0x2000, v220
	s_nop 1
	v_addc_co_u32_e32 v255, vcc, 0, v221, vcc
	global_load_dwordx4 v[132:135], v[220:221], off
	global_load_dwordx4 v[136:139], v[254:255], off
	v_add_f32_e32 v80, v80, v96
	v_add_f32_e32 v81, v81, v97
	v_add_f32_e32 v80, 0, v80
	v_add_f32_e32 v82, v82, v98
	v_mfma_f32_32x32x16_bf16 v[32:47], v[140:143], v[240:243], v[32:47]
	v_add_f32_e32 v80, v81, v80
	v_add_f32_e32 v83, v83, v99
	v_add_f32_e32 v80, v82, v80
	v_add_f32_e32 v84, v84, v100
	v_add_f32_e32 v80, v83, v80
	v_add_f32_e32 v85, v85, v101
	v_add_f32_e32 v80, v84, v80
	v_add_f32_e32 v86, v86, v102
	v_add_f32_e32 v80, v85, v80
	v_add_f32_e32 v87, v87, v103
	v_mfma_f32_32x32x16_bf16 v[16:31], v[148:151], v[240:243], v[16:31]
	v_add_f32_e32 v80, v86, v80
	v_add_f32_e32 v88, v88, v104
	v_add_f32_e32 v80, v87, v80
	v_add_f32_e32 v89, v89, v105
	v_add_f32_e32 v80, v88, v80
	v_add_f32_e32 v90, v90, v106
	v_add_f32_e32 v80, v89, v80
	v_add_f32_e32 v91, v91, v107
	v_add_f32_e32 v80, v90, v80
	v_add_f32_e32 v92, v92, v108
	v_mfma_f32_32x32x16_bf16 v[32:47], v[156:159], v[236:239], v[32:47]
	v_add_f32_e32 v80, v91, v80
	v_add_f32_e32 v93, v93, v109
	v_add_f32_e32 v80, v92, v80
	v_add_f32_e32 v94, v94, v110
	v_add_f32_e32 v80, v93, v80
	v_add_f32_e32 v95, v95, v111
	v_add_f32_e32 v80, v94, v80
	v_add_f32_e32 v80, v95, v80
	v_add_f32_e32 v231, v231, v80
	ds_read_b64_tr_b16 v[80:81], v210 offset:36992
	ds_read_b64_tr_b16 v[82:83], v210 offset:39552
	ds_read_b64_tr_b16 v[84:85], v210 offset:37056
	ds_read_b64_tr_b16 v[86:87], v210 offset:39616
	v_mfma_f32_32x32x16_bf16 v[16:31], v[168:171], v[236:239], v[16:31]
	ds_read_b64_tr_b16 v[88:89], v210 offset:42112
	ds_read_b64_tr_b16 v[90:91], v210 offset:44672
	ds_read_b64_tr_b16 v[92:93], v210 offset:42176
	ds_read_b64_tr_b16 v[94:95], v210 offset:44736
	ds_read_b64_tr_b16 v[96:97], v210 offset:47232
	ds_read_b64_tr_b16 v[98:99], v210 offset:49792
	ds_read_b64_tr_b16 v[100:101], v210 offset:47296
	ds_read_b64_tr_b16 v[102:103], v210 offset:49856
	v_mfma_f32_32x32x16_bf16 v[32:47], v[160:163], v[244:247], v[32:47]
	ds_read_b64_tr_b16 v[104:105], v210 offset:52352
	ds_read_b64_tr_b16 v[106:107], v210 offset:54912
	ds_read_b64_tr_b16 v[108:109], v210 offset:52416
	ds_read_b64_tr_b16 v[110:111], v210 offset:54976
	v_exp_f32_e32 v172, v172
	v_exp_f32_e32 v188, v188
	v_mfma_f32_32x32x16_bf16 v[16:31], v[164:167], v[244:247], v[16:31]
	v_exp_f32_e32 v173, v173
	v_exp_f32_e32 v189, v189
	v_exp_f32_e32 v174, v174
	v_exp_f32_e32 v190, v190
	s_waitcnt lgkmcnt(14)
	v_mfma_f32_32x32x16_bf16 v[64:79], v[80:83], v[232:235], v[64:79]
	ds_read_b64_tr_b16 v[144:145], v252 offset:36864
	ds_read_b64_tr_b16 v[146:147], v252 offset:39424
	v_exp_f32_e32 v175, v175
	v_exp_f32_e32 v191, v191
	v_exp_f32_e32 v176, v176
	v_exp_f32_e32 v192, v192
	s_waitcnt lgkmcnt(14)
	v_mfma_f32_32x32x16_bf16 v[48:63], v[84:87], v[232:235], v[48:63]
	ds_read_b64_tr_b16 v[152:153], v252 offset:36928
	ds_read_b64_tr_b16 v[154:155], v252 offset:39488
	v_exp_f32_e32 v177, v177
	v_exp_f32_e32 v193, v193
	v_exp_f32_e32 v178, v178
	v_exp_f32_e32 v194, v194
	s_waitcnt lgkmcnt(14)
	v_mfma_f32_32x32x16_bf16 v[64:79], v[88:91], v[240:243], v[64:79]
	ds_read_b64_tr_b16 v[140:141], v252 offset:41984
	ds_read_b64_tr_b16 v[142:143], v252 offset:44544
	v_exp_f32_e32 v179, v179
	v_exp_f32_e32 v195, v195
	v_exp_f32_e32 v180, v180
	s_waitcnt lgkmcnt(14)
	v_mfma_f32_32x32x16_bf16 v[48:63], v[92:95], v[240:243], v[48:63]
	ds_read_b64_tr_b16 v[148:149], v252 offset:42048
	ds_read_b64_tr_b16 v[150:151], v252 offset:44608
	v_exp_f32_e32 v196, v196
	v_exp_f32_e32 v181, v181
	v_exp_f32_e32 v197, v197
	s_waitcnt lgkmcnt(14)
	v_mfma_f32_32x32x16_bf16 v[64:79], v[96:99], v[236:239], v[64:79]
	ds_read_b64_tr_b16 v[156:157], v252 offset:47104
	ds_read_b64_tr_b16 v[158:159], v252 offset:49664
	v_exp_f32_e32 v182, v182
	v_exp_f32_e32 v198, v198
	v_exp_f32_e32 v183, v183
	s_waitcnt lgkmcnt(14)
	v_mfma_f32_32x32x16_bf16 v[48:63], v[100:103], v[236:239], v[48:63]
	ds_read_b64_tr_b16 v[168:169], v252 offset:47168
	ds_read_b64_tr_b16 v[170:171], v252 offset:49728
	v_exp_f32_e32 v199, v199
	v_exp_f32_e32 v184, v184
	v_exp_f32_e32 v200, v200
	s_waitcnt lgkmcnt(14)
	v_mfma_f32_32x32x16_bf16 v[64:79], v[104:107], v[244:247], v[64:79]
	ds_read_b64_tr_b16 v[160:161], v252 offset:52224
	ds_read_b64_tr_b16 v[162:163], v252 offset:54784
	v_exp_f32_e32 v185, v185
	v_exp_f32_e32 v201, v201
	v_exp_f32_e32 v186, v186
	s_waitcnt lgkmcnt(14)
; #define ATT_LOADK(t) do { kst[0] = *(const u32x4*)((const char*)KAp + (size_t)(t) * (size_t)(128 * ldka) + offA); \
;     if (HASB) { if (tid < 256) kst[KPT - 1] = *(const u32x4*)((const char*)KBp + (size_t)(t) * (size_t)(128 * ldkb) + offB); } } while (0)
; #define ATT_LOADV(t) do { _Pragma("unroll") for (int i = 0; i < VPT; ++i) vst[i] = *(const u32x4*)((const char*)Vp + ((size_t)(t) * 64 + (size_t)i * (512 / VCH)) * (size_t)(2 * ldv) + offV); } while (0)
; #define ATT_STOREK(sl) do { *(LAS u32x4*)(lds + (sl) * C::KBYTES + ldsA) = kst[0]; \
;     if (HASB) { if (tid < 256) *(LAS u32x4*)(lds + (sl) * C::KBYTES + ldsB) = kst[KPT - 1]; } } while (0)
; #define ATT_STOREV(sl) do { _Pragma("unroll") for (int i = 0; i < VPT; ++i) *(LAS u32x4*)(lds + C::VOFF + (sl) * C::VBYTES + i * (512 / VCH) * VP + ldsV) = vst[i]; } while (0)
; #define ATT_KFRAG(slot) do { LAS const unsigned char* kb_ = lds + (slot) * C::KBYTES + koff; \
;     _Pragma("unroll") for (int d0 = 0; d0 < ND; ++d0) { kf[2 * d0] = *(LAS const bf16x8*)(kb_ + 32 * d0); kf[2 * d0 + 1] = *(LAS const bf16x8*)(kb_ + 32 * KP + 32 * d0); } } while (0)
; template <int DQK, int DKA, int DV> ...
;     ...
;     for (int t = 0; t < NT; ++t) {
;         const int ks1 = (t + 1) & 3;
;         if (t + 3 < NT) ATT_STOREK((t + 3) & 3);
;         if (t + 2 < NT) ATT_STOREV((t + 2) & 3);
;         if (t + 4 < NT) ATT_LOADK(t + 4);
;         if (t + 3 < NT) ATT_LOADV(t + 3);
;     ...
;             if (NV == 2) {
;                 __builtin_amdgcn_s_setprio(3); ATT_PV(0); __builtin_amdgcn_s_setprio(0);
;                 __builtin_amdgcn_sched_barrier(0);
;                 if (t + 1 < NT) ATT_KFRAG(ks1);
;             } else {
;                 __builtin_amdgcn_s_setprio(3); ATT_PV(0); __builtin_amdgcn_s_setprio(0);
;                 __builtin_amdgcn_sched_barrier(0);
;                 ATT_VFRAG(2);
;                 __builtin_amdgcn_sched_barrier(0);
;                 __builtin_amdgcn_s_setprio(3); ATT_PV(2); __builtin_amdgcn_s_setprio(0);
;                 __builtin_amdgcn_sched_barrier(0);
;                 if (t + 1 < NT) ATT_KFRAG(ks1);
;             }
;             __builtin_amdgcn_sched_barrier(0);
;         }
;         if (t & 1) asm volatile("s_waitcnt lgkmcnt(0)\n\ts_barrier" ::: "memory");
	v_mfma_f32_32x32x16_bf16 v[48:63], v[108:111], v[244:247], v[48:63]
	ds_read_b64_tr_b16 v[164:165], v252 offset:52288
	ds_read_b64_tr_b16 v[166:167], v252 offset:54848
	v_exp_f32_e32 v202, v202
	v_exp_f32_e32 v187, v187
	v_exp_f32_e32 v203, v203
	s_setprio 0
	v_cvt_pk_bf16_f32 v232, v172, v173
	v_cvt_pk_bf16_f32 v233, v174, v175
	v_cvt_pk_bf16_f32 v234, v176, v177
	v_cvt_pk_bf16_f32 v235, v178, v179
	v_cvt_pk_bf16_f32 v236, v188, v189
	v_cvt_pk_bf16_f32 v237, v190, v191
	v_cvt_pk_bf16_f32 v238, v192, v193
	v_cvt_pk_bf16_f32 v239, v194, v195
	v_cvt_pk_bf16_f32 v240, v180, v181
	v_cvt_pk_bf16_f32 v241, v182, v183
	v_cvt_pk_bf16_f32 v242, v184, v185
	v_cvt_pk_bf16_f32 v243, v186, v187
	v_cvt_pk_bf16_f32 v244, v196, v197
	v_cvt_pk_bf16_f32 v245, v198, v199
	v_cvt_pk_bf16_f32 v246, v200, v201
	v_cvt_pk_bf16_f32 v247, v202, v203
	v_add_f32_e32 v172, v172, v188
	v_add_f32_e32 v173, v173, v189
	v_add_f32_e32 v172, 0, v172
	v_add_f32_e32 v174, v174, v190
	v_add_f32_e32 v172, v173, v172
	v_add_f32_e32 v175, v175, v191
	v_add_f32_e32 v172, v174, v172
	v_add_f32_e32 v176, v176, v192
	v_add_f32_e32 v172, v175, v172
	v_add_f32_e32 v177, v177, v193
	v_add_f32_e32 v172, v176, v172
	v_add_f32_e32 v178, v178, v194
	s_waitcnt lgkmcnt(0)
	v_mfma_f32_32x32x16_bf16 v[32:47], v[144:147], v[232:235], v[32:47]
	ds_read_b64_tr_b16 v[80:81], v252 offset:36992
	ds_read_b64_tr_b16 v[82:83], v252 offset:39552
	ds_read_b64_tr_b16 v[84:85], v252 offset:37056
	ds_read_b64_tr_b16 v[86:87], v252 offset:39616
	v_add_f32_e32 v172, v177, v172
	v_add_f32_e32 v179, v179, v195
	v_add_f32_e32 v172, v178, v172
	v_mfma_f32_32x32x16_bf16 v[16:31], v[152:155], v[232:235], v[16:31]
	ds_read_b64_tr_b16 v[88:89], v252 offset:42112
	ds_read_b64_tr_b16 v[90:91], v252 offset:44672
	ds_read_b64_tr_b16 v[92:93], v252 offset:42176
	ds_read_b64_tr_b16 v[94:95], v252 offset:44736
	v_add_f32_e32 v180, v180, v196
	v_add_f32_e32 v172, v179, v172
	v_add_f32_e32 v181, v181, v197
	v_mfma_f32_32x32x16_bf16 v[32:47], v[140:143], v[240:243], v[32:47]
	ds_read_b64_tr_b16 v[96:97], v252 offset:47232
	ds_read_b64_tr_b16 v[98:99], v252 offset:49792
	ds_read_b64_tr_b16 v[100:101], v252 offset:47296
	ds_read_b64_tr_b16 v[102:103], v252 offset:49856
	v_add_f32_e32 v172, v180, v172
	v_add_f32_e32 v182, v182, v198
	v_add_f32_e32 v172, v181, v172
	v_mfma_f32_32x32x16_bf16 v[16:31], v[148:151], v[240:243], v[16:31]
	ds_read_b64_tr_b16 v[104:105], v252 offset:52352
	ds_read_b64_tr_b16 v[106:107], v252 offset:54912
	ds_read_b64_tr_b16 v[108:109], v252 offset:52416
	ds_read_b64_tr_b16 v[110:111], v252 offset:54976
	v_add_f32_e32 v183, v183, v199
	v_add_f32_e32 v172, v182, v172
	v_add_f32_e32 v184, v184, v200
	v_mfma_f32_32x32x16_bf16 v[32:47], v[156:159], v[236:239], v[32:47]
	v_add_f32_e32 v172, v183, v172
	v_add_f32_e32 v185, v185, v201
	v_add_f32_e32 v172, v184, v172
	v_mfma_f32_32x32x16_bf16 v[16:31], v[168:171], v[236:239], v[16:31]
	v_add_f32_e32 v186, v186, v202
	v_add_f32_e32 v172, v185, v172
	v_add_f32_e32 v187, v187, v203
	v_mfma_f32_32x32x16_bf16 v[32:47], v[160:163], v[244:247], v[32:47]
	v_add_f32_e32 v172, v186, v172
	v_add_f32_e32 v172, v187, v172
	v_add_f32_e32 v231, v231, v172
	v_mfma_f32_32x32x16_bf16 v[16:31], v[164:167], v[244:247], v[16:31]
	s_add_i32 s1, s1, 2
	s_addk_i32 s79, 0x80
	s_add_i32 s22, s1, -4
	s_and_b32 s22, s22, 3
	s_mulk_i32 s22, 0x2400
	v_add_u32_e32 v249, s22, v226
	s_waitcnt lgkmcnt(0)
	v_mfma_f32_32x32x16_bf16 v[64:79], v[80:83], v[232:235], v[64:79]
	ds_read_b128 v[144:147], v249
	ds_read_b128 v[152:155], v249 offset:4608
	v_mfma_f32_32x32x16_bf16 v[48:63], v[84:87], v[232:235], v[48:63]
	ds_read_b128 v[140:143], v249 offset:32
	ds_read_b128 v[148:151], v249 offset:4640
	v_mfma_f32_32x32x16_bf16 v[64:79], v[88:91], v[240:243], v[64:79]
	ds_read_b128 v[156:159], v249 offset:64
	ds_read_b128 v[168:171], v249 offset:4672
	v_mfma_f32_32x32x16_bf16 v[48:63], v[92:95], v[240:243], v[48:63]
	ds_read_b128 v[160:163], v249 offset:96
	ds_read_b128 v[164:167], v249 offset:4704
	v_mfma_f32_32x32x16_bf16 v[64:79], v[96:99], v[236:239], v[64:79]
	v_lshl_add_u64 v[218:219], v[218:219], 0, s[10:11]
	v_mfma_f32_32x32x16_bf16 v[48:63], v[100:103], v[236:239], v[48:63]
	v_lshl_add_u64 v[220:221], v[220:221], 0, s[8:9]
	v_mfma_f32_32x32x16_bf16 v[64:79], v[104:107], v[244:247], v[64:79]
	v_mfma_f32_32x32x16_bf16 v[48:63], v[108:111], v[244:247], v[48:63]
	s_setprio 0
	s_add_i32 s23, s1, 1
	s_cmp_lt_u32 s23, s16
	s_cbranch_scc0 .Lfast_d_x
	s_add_i32 s50, s1, -4
	s_and_b32 s22, s50, 3
	s_mulk_i32 s22, 0x5000
	v_add_u32_e32 v210, s22, v229
	s_add_i32 s51, s1, -3
	s_and_b32 s22, s51, 3
	s_mul_i32 s23, s22, 0x5000
	s_mulk_i32 s22, 0x2400
	v_add_u32_e32 v249, s22, v226
	v_add_u32_e32 v252, s23, v229
	s_waitcnt lgkmcnt(0)
	s_barrier
	s_setprio 3
	s_branch .Lfast_d_qk
.Lfast_d_x:
	s_waitcnt lgkmcnt(0)
	s_barrier
	s_branch .LBB0_1124
.Lfast_d_bail1:
	s_waitcnt lgkmcnt(0)
	ds_read_b64_tr_b16 v[196:197], v210 offset:36864
	ds_read_b64_tr_b16 v[198:199], v210 offset:39424
	ds_read_b64_tr_b16 v[202:203], v210 offset:39488
	ds_read_b64_tr_b16 v[200:201], v210 offset:36928
	ds_read_b64_tr_b16 v[192:193], v210 offset:41984
	ds_read_b64_tr_b16 v[194:195], v210 offset:44544
	ds_read_b64_tr_b16 v[190:191], v210 offset:44608
	ds_read_b64_tr_b16 v[188:189], v210 offset:42048
	ds_read_b64_tr_b16 v[184:185], v210 offset:47104
	ds_read_b64_tr_b16 v[186:187], v210 offset:49664
	ds_read_b64_tr_b16 v[182:183], v210 offset:49728
	ds_read_b64_tr_b16 v[180:181], v210 offset:47168
	ds_read_b64_tr_b16 v[176:177], v210 offset:52224
	ds_read_b64_tr_b16 v[178:179], v210 offset:54784
	ds_read_b64_tr_b16 v[174:175], v210 offset:54848
	ds_read_b64_tr_b16 v[172:173], v210 offset:52288
	s_branch .Lorig_rare_d
